# TileOrder WGM 2->4 for GEMM1 and GEMM4 (4x8 tiles per XCD round for L2 reuse)
# baseline (speedup 1.0000x reference)
.LBB0_187:
	s_cmpk_lt_i32 s2, 0x500
	v_mov_b32_e32 v10, v218
	s_cselect_b64 s[0:1], -1, 0
	s_cmpk_gt_i32 s2, 0x4ff
	s_nop 0
	v_readfirstlane_b32 s4, v10
	s_cbranch_scc1 .LBB0_189
	s_ashr_i32 s3, s2, 31
	s_lshr_b32 s3, s3, 29
	s_add_i32 s3, s2, s3
	s_ashr_i32 s5, s3, 3
	s_and_b32 s3, s3, -8
	s_sub_i32 s3, s2, s3
	s_cmp_lt_i32 s3, 0
	s_movk_i32 s6, 0xa1
	s_cselect_b32 s6, s6, 0xa0
	s_mul_i32 s3, s3, s6
	s_add_i32 s3, s3, s5
	s_mul_hi_i32 s5, s3, 0x66666667
	s_lshr_b32 s6, s5, 31
	s_ashr_i32 s5, s5, 5
	s_add_i32 s5, s5, s6
	s_lshl_b32 s6, s5, 2
	s_mul_i32 s5, s5, 80
	s_sub_i32 s3, s3, s5
	s_bfe_u32 s5, s3, 0x10007
	s_add_i32 s5, s3, s5
	s_bfe_i32 s7, s5, 0x80000
	s_and_b32 s5, s5, 0xfc
	s_sub_i32 s3, s3, s5
	s_sext_i32_i16 s7, s7
	s_sext_i32_i8 s3, s3
	s_add_i32 s6, s6, s3
	s_ashr_i32 s20, s7, 2

.LBB0_195:
	s_add_i32 s53, s53, 1
	s_mul_i32 s4, s53, s33
	s_mul_hi_u32 s5, s53, s88
	s_add_i32 s5, s5, s4
	s_mul_i32 s4, s53, s88
	s_add_u32 s10, s4, s2
	s_addc_u32 s11, s5, s3
	v_cmp_gt_i64_e32 vcc, s[10:11], v[162:163]
	v_cmp_lt_i64_e64 s[4:5], s[10:11], v[160:161]
	s_cbranch_vccnz .LBB0_197
	s_ashr_i32 s7, s10, 31
	s_lshr_b32 s7, s7, 29
	s_add_i32 s7, s10, s7
	s_ashr_i32 s11, s7, 3
	s_and_b32 s7, s7, -8
	s_sub_i32 s7, s10, s7
	s_cmp_lt_i32 s7, 0
	s_movk_i32 s10, 0xa1
	s_cselect_b32 s10, s10, 0xa0
	s_mul_i32 s7, s7, s10
	s_add_i32 s7, s7, s11
	s_mul_hi_i32 s10, s7, 0x66666667
	s_lshr_b32 s11, s10, 31
	s_ashr_i32 s10, s10, 5
	s_add_i32 s10, s10, s11
	s_lshl_b32 s11, s10, 2
	s_sub_i32 s40, 64, s11
	s_min_i32 s40, s40, 4
	s_abs_i32 s41, s40
	v_cvt_f32_u32_e32 v2, s41
	s_sub_i32 s65, 0, s41
	s_mul_i32 s10, s10, 80
	s_sub_i32 s7, s7, s10
	v_rcp_iflag_f32_e32 v2, v2
	s_abs_i32 s10, s7
	s_xor_b32 s64, s7, s40
	s_ashr_i32 s64, s64, 31
	v_mul_f32_e32 v2, 0x4f7ffffe, v2
	v_cvt_u32_f32_e32 v2, v2
	s_nop 0
	v_readfirstlane_b32 s66, v2
	s_mul_i32 s65, s65, s66
	s_mul_hi_u32 s65, s66, s65
	s_add_i32 s66, s66, s65
	s_mul_hi_u32 s65, s10, s66
	s_mul_i32 s66, s65, s41
	s_sub_i32 s10, s10, s66
	s_add_i32 s67, s65, 1
	s_sub_i32 s66, s10, s41
	s_cmp_ge_u32 s10, s41
	s_cselect_b32 s65, s67, s65
	s_cselect_b32 s10, s66, s10
	s_add_i32 s66, s65, 1
	s_cmp_ge_u32 s10, s41
	s_cselect_b32 s10, s66, s65
	s_xor_b32 s10, s10, s64
	s_sub_i32 s64, s10, s64
	s_mul_i32 s10, s64, s40
	s_sub_i32 s7, s7, s10
	s_add_i32 s66, s11, s7

.LBB0_1116:
	s_mul_i32 s0, s88, 6
	s_mul_hi_i32 s1, s88, 6
	s_add_u32 s0, s0, s2
	s_addc_u32 s1, s1, s3
	v_mov_b64_e32 v[2:3], 0x595
	v_cmp_gt_i64_e64 s[40:41], s[0:1], v[2:3]
	v_mov_b64_e32 v[2:3], 0x596
	s_cmpk_lt_i32 s2, 0x596
	v_cmp_lt_i64_e64 s[10:11], s[0:1], v[2:3]
	s_cselect_b64 s[4:5], -1, 0
	s_lshr_b32 s0, s3, 29
	s_add_i32 s0, s2, s0
	s_ashr_i32 s51, s0, 3
	s_and_b32 s0, s0, -8
	s_sub_i32 s52, s2, s0
	s_cmp_lt_i32 s52, 6
	s_mul_i32 s14, s52, 0xb2
	s_cselect_b64 s[8:9], -1, 0
	s_add_i32 s14, s14, 6
	s_mul_i32 s15, s52, 0xb3
	v_writelane_b32 v251, s10, 4
	s_and_b64 vcc, exec, s[10:11]
	s_waitcnt lgkmcnt(0)
	v_writelane_b32 v251, s11, 5
	s_cbranch_vccnz .LBB0_1151
	v_mov_b32_e32 v2, v218
	s_movk_i32 s0, 0x100
	s_nop 0
	v_cmp_gt_i32_e32 vcc, s0, v2
	s_and_saveexec_b64 s[0:1], vcc
	s_cbranch_execz .LBB0_1150
	s_mov_b32 s98, 0
	s_add_i32 s10, 0, 0x22000
	v_lshl_add_u32 v1, v2, 2, s10
	s_andn2_b64 vcc, exec, s[4:5]
	v_add_u32_e32 v4, -2, v2
	s_cbranch_vccnz .LBB0_1120
	s_and_b64 s[10:11], s[8:9], exec
	s_cselect_b32 s10, s15, s14
	s_add_i32 s10, s10, s51
	s_mul_hi_i32 s11, s10, 0x2e8ba2e9
	s_lshr_b32 s12, s11, 31
	s_ashr_i32 s11, s11, 4
	s_add_i32 s11, s11, s12
	s_lshl_b32 s12, s11, 2
	s_sub_i32 s13, 0x41, s12
	s_min_i32 s13, s13, 4
	s_abs_i32 s13, s13
	v_cvt_f32_u32_e32 v2, s13
	s_sub_i32 s16, 0, s13
	s_mul_i32 s11, s11, 88
	s_sub_i32 s10, s10, s11
	v_rcp_iflag_f32_e32 v2, v2
	s_ashr_i32 s11, s10, 31
	s_abs_i32 s10, s10
	v_mov_b32_e32 v3, 0x3fff
	v_mul_f32_e32 v2, 0x4f7ffffe, v2
	v_cvt_u32_f32_e32 v2, v2
	s_nop 0
	v_readfirstlane_b32 s17, v2
	s_mul_i32 s16, s16, s17
	s_mul_hi_u32 s16, s17, s16
	s_add_i32 s17, s17, s16
	s_mul_hi_u32 s16, s10, s17
	s_mul_i32 s16, s16, s13
	s_sub_i32 s10, s10, s16
	s_sub_i32 s16, s10, s13
	s_cmp_ge_u32 s10, s13
	s_cselect_b32 s10, s16, s10
	s_sub_i32 s16, s10, s13
	s_cmp_ge_u32 s10, s13
	s_cselect_b32 s10, s16, s10
	s_xor_b32 s10, s10, s11
	s_sub_i32 s10, s10, s11
	s_add_i32 s10, s12, s10
	s_mulk_i32 s10, 0xfe
	v_add_u32_e32 v2, s10, v4
	v_med3_i32 v2, v2, 0, v3
	v_lshlrev_b32_e32 v2, 6, v2
	global_load_dwordx4 v[100:103], v2, s[66:67]
	global_load_dwordx4 v[104:107], v2, s[66:67] offset:16
	global_load_dwordx4 v[108:111], v2, s[66:67] offset:32
	global_load_dwordx4 v[112:115], v2, s[66:67] offset:48
	v_readlane_b32 s16, v251, 2
	v_readlane_b32 s17, v251, 3
	s_or_b32 s98, s98, 1

.LBB0_1125:
	s_add_i32 s12, s18, s12
	s_mul_hi_i32 s13, s12, 0x2e8ba2e9
	s_lshr_b32 s16, s13, 31
	s_ashr_i32 s13, s13, 4
	s_add_i32 s13, s13, s16
	s_lshl_b32 s16, s13, 2
	s_sub_i32 s17, 0x41, s16
	s_min_i32 s17, s17, 4
	s_abs_i32 s17, s17
	v_cvt_f32_u32_e32 v5, s17
	s_sub_i32 s18, 0, s17
	s_mul_i32 s13, s13, 88
	s_sub_i32 s12, s12, s13
	v_rcp_iflag_f32_e32 v5, v5
	s_ashr_i32 s13, s12, 31
	s_abs_i32 s12, s12
	v_mov_b32_e32 v6, 0x3fff
	v_mul_f32_e32 v5, 0x4f7ffffe, v5
	v_cvt_u32_f32_e32 v5, v5
	s_nop 0
	v_readfirstlane_b32 s19, v5
	s_mul_i32 s18, s18, s19
	s_mul_hi_u32 s18, s19, s18
	s_add_i32 s19, s19, s18
	s_mul_hi_u32 s18, s12, s19
	s_mul_i32 s18, s18, s17
	s_sub_i32 s12, s12, s18
	s_sub_i32 s18, s12, s17
	s_cmp_ge_u32 s12, s17
	s_cselect_b32 s12, s18, s12
	s_sub_i32 s18, s12, s17
	s_cmp_ge_u32 s12, s17
	s_cselect_b32 s12, s18, s12
	s_xor_b32 s12, s12, s13
	s_sub_i32 s12, s12, s13
	s_add_i32 s12, s16, s12
	s_mulk_i32 s12, 0xfe
	v_add_u32_e32 v5, s12, v4
	v_med3_i32 v5, v5, 0, v6
	v_lshlrev_b32_e32 v5, 6, v5
	global_load_dwordx4 v[116:119], v5, s[66:67]
	global_load_dwordx4 v[120:123], v5, s[66:67] offset:16
	global_load_dwordx4 v[124:127], v5, s[66:67] offset:32
	global_load_dwordx4 v[128:131], v5, s[66:67] offset:48
	v_readlane_b32 s18, v251, 58
	v_readlane_b32 s16, v251, 2
	v_readlane_b32 s19, v251, 59
	v_readlane_b32 s17, v251, 3
	s_or_b32 s98, s98, 2

.LBB0_1131:
	s_add_i32 s12, s18, s12
	s_mul_hi_i32 s13, s12, 0x2e8ba2e9
	s_lshr_b32 s16, s13, 31
	s_ashr_i32 s13, s13, 4
	s_add_i32 s13, s13, s16
	s_lshl_b32 s16, s13, 2
	s_sub_i32 s17, 0x41, s16
	s_min_i32 s17, s17, 4
	s_abs_i32 s17, s17
	v_cvt_f32_u32_e32 v2, s17
	s_sub_i32 s18, 0, s17
	s_mul_i32 s13, s13, 88
	s_sub_i32 s12, s12, s13
	v_rcp_iflag_f32_e32 v2, v2
	s_ashr_i32 s13, s12, 31
	s_abs_i32 s12, s12
	v_mov_b32_e32 v3, 0x3fff
	v_mul_f32_e32 v2, 0x4f7ffffe, v2
	v_cvt_u32_f32_e32 v2, v2
	s_nop 0
	v_readfirstlane_b32 s19, v2
	s_mul_i32 s18, s18, s19
	s_mul_hi_u32 s18, s19, s18
	s_add_i32 s19, s19, s18
	s_mul_hi_u32 s18, s12, s19
	s_mul_i32 s18, s18, s17
	s_sub_i32 s12, s12, s18
	s_sub_i32 s18, s12, s17
	s_cmp_ge_u32 s12, s17
	s_cselect_b32 s12, s18, s12
	s_sub_i32 s18, s12, s17
	s_cmp_ge_u32 s12, s17
	s_cselect_b32 s12, s18, s12
	s_xor_b32 s12, s12, s13
	s_sub_i32 s12, s12, s13
	s_add_i32 s12, s16, s12
	s_mulk_i32 s12, 0xfe
	v_add_u32_e32 v2, s12, v4
	v_med3_i32 v2, v2, 0, v3
	v_lshlrev_b32_e32 v2, 6, v2
	global_load_dwordx4 v[132:135], v2, s[66:67]
	global_load_dwordx4 v[136:139], v2, s[66:67] offset:16
	global_load_dwordx4 v[140:143], v2, s[66:67] offset:32
	global_load_dwordx4 v[144:147], v2, s[66:67] offset:48
	v_readlane_b32 s18, v251, 58
	v_readlane_b32 s16, v251, 2
	v_readlane_b32 s19, v251, 59
	v_readlane_b32 s17, v251, 3
	s_or_b32 s98, s98, 4

.LBB0_1137:
	s_add_i32 s12, s18, s12
	s_mul_hi_i32 s13, s12, 0x2e8ba2e9
	s_lshr_b32 s16, s13, 31
	s_ashr_i32 s13, s13, 4
	s_add_i32 s13, s13, s16
	s_lshl_b32 s16, s13, 2
	s_sub_i32 s17, 0x41, s16
	s_min_i32 s17, s17, 4
	s_abs_i32 s17, s17
	v_cvt_f32_u32_e32 v5, s17
	s_sub_i32 s18, 0, s17
	s_mul_i32 s13, s13, 88
	s_sub_i32 s12, s12, s13
	v_rcp_iflag_f32_e32 v5, v5
	s_ashr_i32 s13, s12, 31
	s_abs_i32 s12, s12
	v_mov_b32_e32 v6, 0x3fff
	v_mul_f32_e32 v5, 0x4f7ffffe, v5
	v_cvt_u32_f32_e32 v5, v5
	s_nop 0
	v_readfirstlane_b32 s19, v5
	s_mul_i32 s18, s18, s19
	s_mul_hi_u32 s18, s19, s18
	s_add_i32 s19, s19, s18
	s_mul_hi_u32 s18, s12, s19
	s_mul_i32 s18, s18, s17
	s_sub_i32 s12, s12, s18
	s_sub_i32 s18, s12, s17
	s_cmp_ge_u32 s12, s17
	s_cselect_b32 s12, s18, s12
	s_sub_i32 s18, s12, s17
	s_cmp_ge_u32 s12, s17
	s_cselect_b32 s12, s18, s12
	s_xor_b32 s12, s12, s13
	s_sub_i32 s12, s12, s13
	s_add_i32 s12, s16, s12
	s_mulk_i32 s12, 0xfe
	v_add_u32_e32 v5, s12, v4
	v_med3_i32 v5, v5, 0, v6
	v_lshlrev_b32_e32 v5, 6, v5
	global_load_dwordx4 v[148:151], v5, s[66:67]
	global_load_dwordx4 v[152:155], v5, s[66:67] offset:16
	global_load_dwordx4 v[156:159], v5, s[66:67] offset:32
	global_load_dwordx4 v[160:163], v5, s[66:67] offset:48
	v_readlane_b32 s18, v251, 58
	v_readlane_b32 s16, v251, 2
	v_readlane_b32 s19, v251, 59
	v_readlane_b32 s17, v251, 3
	s_or_b32 s98, s98, 8

.LBB0_1143:
	s_add_i32 s12, s18, s12
	s_mul_hi_i32 s13, s12, 0x2e8ba2e9
	s_lshr_b32 s16, s13, 31
	s_ashr_i32 s13, s13, 4
	s_add_i32 s13, s13, s16
	s_lshl_b32 s16, s13, 2
	s_sub_i32 s17, 0x41, s16
	s_min_i32 s17, s17, 4
	s_abs_i32 s17, s17
	v_cvt_f32_u32_e32 v2, s17
	s_sub_i32 s18, 0, s17
	s_mul_i32 s13, s13, 88
	s_sub_i32 s12, s12, s13
	v_rcp_iflag_f32_e32 v2, v2
	s_ashr_i32 s13, s12, 31
	s_abs_i32 s12, s12
	v_mov_b32_e32 v3, 0x3fff
	v_mul_f32_e32 v2, 0x4f7ffffe, v2
	v_cvt_u32_f32_e32 v2, v2
	s_nop 0
	v_readfirstlane_b32 s19, v2
	s_mul_i32 s18, s18, s19
	s_mul_hi_u32 s18, s19, s18
	s_add_i32 s19, s19, s18
	s_mul_hi_u32 s18, s12, s19
	s_mul_i32 s18, s18, s17
	s_sub_i32 s12, s12, s18
	s_sub_i32 s18, s12, s17
	s_cmp_ge_u32 s12, s17
	s_cselect_b32 s12, s18, s12
	s_sub_i32 s18, s12, s17
	s_cmp_ge_u32 s12, s17
	s_cselect_b32 s12, s18, s12
	s_xor_b32 s12, s12, s13
	s_sub_i32 s12, s12, s13
	s_add_i32 s12, s16, s12
	s_mulk_i32 s12, 0xfe
	v_add_u32_e32 v2, s12, v4
	v_med3_i32 v2, v2, 0, v3
	v_lshlrev_b32_e32 v2, 6, v2
	global_load_dwordx4 v[164:167], v2, s[66:67]
	global_load_dwordx4 v[168:171], v2, s[66:67] offset:16
	global_load_dwordx4 v[172:175], v2, s[66:67] offset:32
	global_load_dwordx4 v[176:179], v2, s[66:67] offset:48
	v_readlane_b32 s18, v251, 58
	v_readlane_b32 s16, v251, 2
	v_readlane_b32 s19, v251, 59
	v_readlane_b32 s17, v251, 3
	s_or_b32 s98, s98, 16

.LBB0_1149:
	s_add_i32 s10, s16, s10
	s_mul_hi_i32 s11, s10, 0x2e8ba2e9
	s_lshr_b32 s12, s11, 31
	s_ashr_i32 s11, s11, 4
	s_add_i32 s11, s11, s12
	s_lshl_b32 s12, s11, 2
	s_sub_i32 s13, 0x41, s12
	s_min_i32 s13, s13, 4
	s_abs_i32 s13, s13
	v_cvt_f32_u32_e32 v2, s13
	s_sub_i32 s16, 0, s13
	s_mul_i32 s11, s11, 88
	s_sub_i32 s10, s10, s11
	v_rcp_iflag_f32_e32 v2, v2
	s_ashr_i32 s11, s10, 31
	s_abs_i32 s10, s10
	v_mov_b32_e32 v3, 0x3fff
	v_mul_f32_e32 v2, 0x4f7ffffe, v2
	v_cvt_u32_f32_e32 v2, v2
	s_nop 0
	v_readfirstlane_b32 s17, v2
	s_mul_i32 s16, s16, s17
	s_mul_hi_u32 s16, s17, s16
	s_add_i32 s17, s17, s16
	s_mul_hi_u32 s16, s10, s17
	s_mul_i32 s16, s16, s13
	s_sub_i32 s10, s10, s16
	s_sub_i32 s16, s10, s13
	s_cmp_ge_u32 s10, s13
	s_cselect_b32 s10, s16, s10
	s_sub_i32 s16, s10, s13
	s_cmp_ge_u32 s10, s13
	s_cselect_b32 s10, s16, s10
	s_xor_b32 s10, s10, s11
	s_sub_i32 s10, s10, s11
	s_add_i32 s10, s12, s10
	s_mulk_i32 s10, 0xfe
	v_add_u32_e32 v2, s10, v4
	v_med3_i32 v2, v2, 0, v3
	v_lshlrev_b32_e32 v14, 6, v2
	global_load_dwordx4 v[180:183], v14, s[66:67]
	global_load_dwordx4 v[184:187], v14, s[66:67] offset:16
	global_load_dwordx4 v[188:191], v14, s[66:67] offset:32
	s_nop 0
	global_load_dwordx4 v[192:195], v14, s[66:67] offset:48
	v_readlane_b32 s16, v251, 2
	v_readlane_b32 s17, v251, 3
	s_or_b32 s98, s98, 32

.LBB0_1165:
	s_and_b64 s[4:5], s[8:9], exec
	s_cselect_b32 s4, s15, s14
	s_add_i32 s4, s4, s51
	s_mul_hi_i32 s5, s4, 0x2e8ba2e9
	s_lshr_b32 s8, s5, 31
	s_ashr_i32 s5, s5, 4
	s_add_i32 s5, s5, s8
	s_lshl_b32 s8, s5, 2
	s_sub_i32 s9, 0x41, s8
	s_min_u32 s9, s9, 4
	s_mul_i32 s5, s5, 88
	s_sub_i32 s11, s4, s5
	v_cvt_f32_ubyte0_e32 v3, s9
	v_cvt_f32_i32_e32 v2, s11
	v_rcp_iflag_f32_e32 v4, v3
	s_ashr_i32 s4, s11, 30
	s_or_b32 s12, s4, 1
	v_mul_f32_e32 v4, v2, v4
	v_trunc_f32_e32 v4, v4
	v_fma_f32 v2, -v4, v3, v2
	v_cvt_i32_f32_e32 v4, v4
	v_cmp_ge_f32_e64 s[4:5], |v2|, v3
	s_and_b64 s[4:5], s[4:5], exec
	s_cselect_b32 s4, s12, 0
	v_readfirstlane_b32 s5, v4
	s_add_i32 s4, s5, s4
	s_sext_i32_i8 s72, s4
	s_mul_i32 s4, s4, s9
	s_sub_i32 s4, s11, s4
	s_sext_i32_i8 s4, s4
	s_add_i32 s37, s8, s4
	s_and_b64 vcc, exec, s[0:1]
	s_cbranch_vccnz .LBB0_1153

.LBB0_1176:
	s_ashr_i32 s16, s19, 3
	s_add_i32 s16, s20, s16
	s_mul_hi_i32 s17, s16, 0x2e8ba2e9
	s_lshr_b32 s18, s17, 31
	s_ashr_i32 s17, s17, 4
	s_add_i32 s17, s17, s18
	s_lshl_b32 s18, s17, 2
	s_sub_i32 s19, 0x41, s18
	s_min_i32 s19, s19, 4
	s_abs_i32 s20, s19
	v_cvt_f32_u32_e32 v2, s20
	s_sub_i32 s36, 0, s20
	s_mul_i32 s17, s17, 88
	s_sub_i32 s17, s16, s17
	v_rcp_iflag_f32_e32 v2, v2
	s_abs_i32 s16, s17
	s_xor_b32 s21, s17, s19
	s_ashr_i32 s21, s21, 31
	v_mul_f32_e32 v2, 0x4f7ffffe, v2
	v_cvt_u32_f32_e32 v2, v2
	s_nop 0
	v_readfirstlane_b32 s38, v2
	s_mul_i32 s36, s36, s38
	s_mul_hi_u32 s36, s38, s36
	s_add_i32 s38, s38, s36
	s_mul_hi_u32 s36, s16, s38
	s_mul_i32 s38, s36, s20
	s_sub_i32 s16, s16, s38
	s_add_i32 s39, s36, 1
	s_sub_i32 s38, s16, s20
	s_cmp_ge_u32 s16, s20
	s_cselect_b32 s36, s39, s36
	s_cselect_b32 s16, s38, s16
	s_add_i32 s38, s36, 1
	s_cmp_ge_u32 s16, s20
	s_cselect_b32 s16, s38, s36
	s_xor_b32 s16, s16, s21
	s_sub_i32 s16, s16, s21
	s_mul_i32 s19, s16, s19
	s_sub_i32 s17, s17, s19
	s_add_i32 s36, s18, s17
